# norm2 (NY=1) row loop hand-pipelined: all 8 loads of a row issued together, next row prefetched before the reduction, counted vmcnt
# speedup vs baseline: 1.0440x; 1.0440x over previous
.LBB0_116:
	global_load_dwordx4 v[68:71], v[66:67], off offset:-3072 nt
	global_load_dwordx4 v[72:75], v[66:67], off offset:-2048 nt
	global_load_dwordx4 v[88:91], v[66:67], off offset:-1024 nt
	global_load_dwordx4 v[92:95], v[66:67], off nt
	global_load_dwordx2 v[96:97], v[64:65], off nt
	global_load_dwordx2 v[98:99], v[64:65], off offset:512 nt
	global_load_dwordx2 v[100:101], v[64:65], off offset:1024 nt
	global_load_dwordx2 v[102:103], v[64:65], off offset:1536 nt
	v_add_co_u32_e32 v122, vcc, 0xec800000, v64
	v_add_u32_e32 v86, s14, v86
	s_nop 0
	v_addc_co_u32_e32 v123, vcc, -1, v65, vcc
	v_lshl_add_u64 v[66:67], v[66:67], 0, s[6:7]
	v_lshl_add_u64 v[64:65], v[64:65], 0, s[2:3]
	v_cmp_lt_i32_e64 s[12:13], v86, v77
	s_nop 1
	s_and_b64 vcc, exec, s[12:13]
	s_cbranch_vccz .Lnrm1_nonext_first
	global_load_dwordx4 v[140:143], v[66:67], off offset:-3072 nt
	global_load_dwordx4 v[144:147], v[66:67], off offset:-2048 nt
	global_load_dwordx4 v[148:151], v[66:67], off offset:-1024 nt
	global_load_dwordx4 v[152:155], v[66:67], off nt
	global_load_dwordx2 v[156:157], v[64:65], off nt
	global_load_dwordx2 v[158:159], v[64:65], off offset:512 nt
	global_load_dwordx2 v[160:161], v[64:65], off offset:1024 nt
	global_load_dwordx2 v[162:163], v[64:65], off offset:1536 nt
	s_waitcnt vmcnt(8)
	s_branch .Lnrm1_go_first
.Lnrm1_nonext_first:
	s_waitcnt vmcnt(0)
	s_branch .Lnrm1_go_a

.Lnrm1_loop:
	v_add_co_u32_e32 v122, vcc, 0xec800000, v64
	v_add_u32_e32 v86, s14, v86
	s_nop 0
	v_addc_co_u32_e32 v123, vcc, -1, v65, vcc
	v_lshl_add_u64 v[66:67], v[66:67], 0, s[6:7]
	v_lshl_add_u64 v[64:65], v[64:65], 0, s[2:3]
	v_cmp_lt_i32_e64 s[12:13], v86, v77
	s_nop 1
	s_and_b64 vcc, exec, s[12:13]
	s_cbranch_vccz .Lnrm1_nonext_a
	global_load_dwordx4 v[140:143], v[66:67], off offset:-3072 nt
	global_load_dwordx4 v[144:147], v[66:67], off offset:-2048 nt
	global_load_dwordx4 v[148:151], v[66:67], off offset:-1024 nt
	global_load_dwordx4 v[152:155], v[66:67], off nt
	global_load_dwordx2 v[156:157], v[64:65], off nt
	global_load_dwordx2 v[158:159], v[64:65], off offset:512 nt
	global_load_dwordx2 v[160:161], v[64:65], off offset:1024 nt
	global_load_dwordx2 v[162:163], v[64:65], off offset:1536 nt
	s_waitcnt vmcnt(12)
	s_branch .Lnrm1_go_a
.Lnrm1_nonext_a:
	s_waitcnt vmcnt(4)
.Lnrm1_go_a:
	v_lshlrev_b32_e32 v106, 16, v96
	v_and_b32_e32 v107, 0xffff0000, v96
	v_lshlrev_b32_e32 v108, 16, v97
	v_and_b32_e32 v109, 0xffff0000, v97
	v_pk_fma_f32 v[68:69], v[44:45], v[106:107], v[68:69]
	v_pk_fma_f32 v[70:71], v[46:47], v[108:109], v[70:71]
	v_lshlrev_b32_e32 v106, 16, v98
	v_and_b32_e32 v107, 0xffff0000, v98
	v_lshlrev_b32_e32 v108, 16, v99
	v_and_b32_e32 v109, 0xffff0000, v99
	v_pk_fma_f32 v[72:73], v[40:41], v[106:107], v[72:73]
	v_pk_fma_f32 v[74:75], v[42:43], v[108:109], v[74:75]
	v_lshlrev_b32_e32 v106, 16, v100
	v_and_b32_e32 v107, 0xffff0000, v100
	v_lshlrev_b32_e32 v108, 16, v101
	v_and_b32_e32 v109, 0xffff0000, v101
	v_pk_fma_f32 v[88:89], v[36:37], v[106:107], v[88:89]
	v_pk_fma_f32 v[90:91], v[38:39], v[108:109], v[90:91]
	v_lshlrev_b32_e32 v106, 16, v102
	v_and_b32_e32 v107, 0xffff0000, v102
	v_lshlrev_b32_e32 v108, 16, v103
	v_and_b32_e32 v109, 0xffff0000, v103
	v_pk_fma_f32 v[92:93], v[32:33], v[106:107], v[92:93]
	v_pk_fma_f32 v[94:95], v[34:35], v[108:109], v[94:95]
	v_mul_f32_e32 v111, v69, v69
	v_fma_f32 v110, v68, v68, v111
	v_mul_f32_e32 v111, v71, v71
	v_fma_f32 v111, v70, v70, v111
	v_add_f32_e32 v112, v110, v111
	v_mul_f32_e32 v111, v73, v73
	v_fma_f32 v110, v72, v72, v111
	v_mul_f32_e32 v111, v75, v75
	v_fma_f32 v111, v74, v74, v111
	v_add_f32_e32 v113, v110, v111
	v_mul_f32_e32 v111, v89, v89
	v_fma_f32 v110, v88, v88, v111
	v_mul_f32_e32 v111, v91, v91
	v_fma_f32 v111, v90, v90, v111
	v_add_f32_e32 v114, v110, v111
	v_mul_f32_e32 v110, v92, v92
	v_mul_f32_e32 v111, v93, v93
	v_add_f32_e32 v110, v110, v111
	v_mul_f32_e32 v111, v94, v94
	v_mul_f32_e32 v115, v95, v95
	v_add_f32_e32 v111, v111, v115
	v_add_f32_e32 v115, v110, v111
	v_add_f32_e32 v112, v112, v113
	v_add_f32_e32 v112, v112, v114
	v_add_f32_e32 v112, v112, v115
	ds_bpermute_b32 v124, v80, v112
	s_waitcnt lgkmcnt(0)
	v_add_f32_e32 v112, v112, v124
	ds_bpermute_b32 v124, v81, v112
	s_waitcnt lgkmcnt(0)
	v_add_f32_e32 v112, v112, v124
	ds_bpermute_b32 v124, v82, v112
	s_waitcnt lgkmcnt(0)
	v_add_f32_e32 v112, v112, v124
	ds_bpermute_b32 v124, v83, v112
	s_waitcnt lgkmcnt(0)
	v_add_f32_e32 v112, v112, v124
	ds_bpermute_b32 v124, v84, v112
	s_waitcnt lgkmcnt(0)
	v_add_f32_e32 v112, v112, v124
	ds_bpermute_b32 v124, v85, v112
	s_waitcnt lgkmcnt(0)
	v_add_f32_e32 v112, v112, v124
	v_fmamk_f32 v112, v112, 0x3a800000, v201
	v_cmp_gt_f32_e32 vcc, s16, v112
	v_mul_f32_e32 v124, 0x4b800000, v112
	s_nop 0
	v_cndmask_b32_e32 v112, v112, v124, vcc
	v_rsq_f32_e32 v116, v112
	s_nop 0
	v_mul_f32_e32 v124, 0x45800000, v116
	v_cndmask_b32_e32 v116, v116, v124, vcc
	v_pk_mul_f32 v[106:107], v[68:69], v[116:117] op_sel_hi:[1,0]
	v_pk_mul_f32 v[108:109], v[70:71], v[116:117] op_sel_hi:[1,0]
	v_pk_mul_f32 v[106:107], v[0:1], v[106:107]
	v_pk_mul_f32 v[108:109], v[2:3], v[108:109]
	v_pk_fma_f32 v[106:107], v[50:51], v[106:107], v[16:17]
	v_pk_fma_f32 v[108:109], v[48:49], v[108:109], v[18:19]
	v_cvt_pk_bf16_f32 v120, v106, v107
	v_cvt_pk_bf16_f32 v121, v108, v109
	global_store_dwordx2 v[122:123], v[120:121], off
	v_pk_mul_f32 v[106:107], v[72:73], v[116:117] op_sel_hi:[1,0]
	v_pk_mul_f32 v[108:109], v[74:75], v[116:117] op_sel_hi:[1,0]
	v_pk_mul_f32 v[106:107], v[4:5], v[106:107]
	v_pk_mul_f32 v[108:109], v[6:7], v[108:109]
	v_pk_fma_f32 v[106:107], v[54:55], v[106:107], v[20:21]
	v_pk_fma_f32 v[108:109], v[52:53], v[108:109], v[22:23]
	v_cvt_pk_bf16_f32 v118, v106, v107
	v_cvt_pk_bf16_f32 v119, v108, v109
	global_store_dwordx2 v[122:123], v[118:119], off offset:512
	v_pk_mul_f32 v[106:107], v[88:89], v[116:117] op_sel_hi:[1,0]
	v_pk_mul_f32 v[108:109], v[90:91], v[116:117] op_sel_hi:[1,0]
	v_pk_mul_f32 v[106:107], v[8:9], v[106:107]
	v_pk_mul_f32 v[108:109], v[10:11], v[108:109]
	v_pk_fma_f32 v[106:107], v[58:59], v[106:107], v[24:25]
	v_pk_fma_f32 v[108:109], v[56:57], v[108:109], v[26:27]
	v_cvt_pk_bf16_f32 v120, v106, v107
	v_cvt_pk_bf16_f32 v121, v108, v109
	global_store_dwordx2 v[122:123], v[120:121], off offset:1024
	v_pk_mul_f32 v[106:107], v[92:93], v[116:117] op_sel_hi:[1,0]
	v_pk_mul_f32 v[108:109], v[94:95], v[116:117] op_sel_hi:[1,0]
	v_pk_mul_f32 v[106:107], v[12:13], v[106:107]
	v_pk_mul_f32 v[108:109], v[14:15], v[108:109]
	v_pk_fma_f32 v[106:107], v[62:63], v[106:107], v[28:29]
	v_pk_fma_f32 v[108:109], v[60:61], v[108:109], v[30:31]
	v_cvt_pk_bf16_f32 v118, v106, v107
	v_cvt_pk_bf16_f32 v119, v108, v109
	global_store_dwordx2 v[122:123], v[118:119], off offset:1536
	s_and_b64 vcc, exec, s[12:13]
	s_cbranch_vccz .Lnrm1_done
	v_add_co_u32_e32 v122, vcc, 0xec800000, v64
	v_add_u32_e32 v86, s14, v86
	s_nop 0
	v_addc_co_u32_e32 v123, vcc, -1, v65, vcc
	v_lshl_add_u64 v[66:67], v[66:67], 0, s[6:7]
	v_lshl_add_u64 v[64:65], v[64:65], 0, s[2:3]
	v_cmp_lt_i32_e64 s[12:13], v86, v77
	s_nop 1
	s_and_b64 vcc, exec, s[12:13]
	s_cbranch_vccz .Lnrm1_nonext_b
	global_load_dwordx4 v[68:71], v[66:67], off offset:-3072 nt
	global_load_dwordx4 v[72:75], v[66:67], off offset:-2048 nt
	global_load_dwordx4 v[88:91], v[66:67], off offset:-1024 nt
	global_load_dwordx4 v[92:95], v[66:67], off nt
	global_load_dwordx2 v[96:97], v[64:65], off nt
	global_load_dwordx2 v[98:99], v[64:65], off offset:512 nt
	global_load_dwordx2 v[100:101], v[64:65], off offset:1024 nt
	global_load_dwordx2 v[102:103], v[64:65], off offset:1536 nt
	s_waitcnt vmcnt(12)
	s_branch .Lnrm1_go_b

.Lnrm1_go_b:
	v_lshlrev_b32_e32 v106, 16, v156
	v_and_b32_e32 v107, 0xffff0000, v156
	v_lshlrev_b32_e32 v108, 16, v157
	v_and_b32_e32 v109, 0xffff0000, v157
	v_pk_fma_f32 v[140:141], v[44:45], v[106:107], v[140:141]
	v_pk_fma_f32 v[142:143], v[46:47], v[108:109], v[142:143]
	v_lshlrev_b32_e32 v106, 16, v158
	v_and_b32_e32 v107, 0xffff0000, v158
	v_lshlrev_b32_e32 v108, 16, v159
	v_and_b32_e32 v109, 0xffff0000, v159
	v_pk_fma_f32 v[144:145], v[40:41], v[106:107], v[144:145]
	v_pk_fma_f32 v[146:147], v[42:43], v[108:109], v[146:147]
	v_lshlrev_b32_e32 v106, 16, v160
	v_and_b32_e32 v107, 0xffff0000, v160
	v_lshlrev_b32_e32 v108, 16, v161
	v_and_b32_e32 v109, 0xffff0000, v161
	v_pk_fma_f32 v[148:149], v[36:37], v[106:107], v[148:149]
	v_pk_fma_f32 v[150:151], v[38:39], v[108:109], v[150:151]
	v_lshlrev_b32_e32 v106, 16, v162
	v_and_b32_e32 v107, 0xffff0000, v162
	v_lshlrev_b32_e32 v108, 16, v163
	v_and_b32_e32 v109, 0xffff0000, v163
	v_pk_fma_f32 v[152:153], v[32:33], v[106:107], v[152:153]
	v_pk_fma_f32 v[154:155], v[34:35], v[108:109], v[154:155]
	v_mul_f32_e32 v111, v141, v141
	v_fma_f32 v110, v140, v140, v111
	v_mul_f32_e32 v111, v143, v143
	v_fma_f32 v111, v142, v142, v111
	v_add_f32_e32 v112, v110, v111
	v_mul_f32_e32 v111, v145, v145
	v_fma_f32 v110, v144, v144, v111
	v_mul_f32_e32 v111, v147, v147
	v_fma_f32 v111, v146, v146, v111
	v_add_f32_e32 v113, v110, v111
	v_mul_f32_e32 v111, v149, v149
	v_fma_f32 v110, v148, v148, v111
	v_mul_f32_e32 v111, v151, v151
	v_fma_f32 v111, v150, v150, v111
	v_add_f32_e32 v114, v110, v111
	v_mul_f32_e32 v110, v152, v152
	v_mul_f32_e32 v111, v153, v153
	v_add_f32_e32 v110, v110, v111
	v_mul_f32_e32 v111, v154, v154
	v_mul_f32_e32 v115, v155, v155
	v_add_f32_e32 v111, v111, v115
	v_add_f32_e32 v115, v110, v111
	v_add_f32_e32 v112, v112, v113
	v_add_f32_e32 v112, v112, v114
	v_add_f32_e32 v112, v112, v115
	ds_bpermute_b32 v124, v80, v112
	s_waitcnt lgkmcnt(0)
	v_add_f32_e32 v112, v112, v124
	ds_bpermute_b32 v124, v81, v112
	s_waitcnt lgkmcnt(0)
	v_add_f32_e32 v112, v112, v124
	ds_bpermute_b32 v124, v82, v112
	s_waitcnt lgkmcnt(0)
	v_add_f32_e32 v112, v112, v124
	ds_bpermute_b32 v124, v83, v112
	s_waitcnt lgkmcnt(0)
	v_add_f32_e32 v112, v112, v124
	ds_bpermute_b32 v124, v84, v112
	s_waitcnt lgkmcnt(0)
	v_add_f32_e32 v112, v112, v124
	ds_bpermute_b32 v124, v85, v112
	s_waitcnt lgkmcnt(0)
	v_add_f32_e32 v112, v112, v124
	v_fmamk_f32 v112, v112, 0x3a800000, v201
	v_cmp_gt_f32_e32 vcc, s16, v112
	v_mul_f32_e32 v124, 0x4b800000, v112
	s_nop 0
	v_cndmask_b32_e32 v112, v112, v124, vcc
	v_rsq_f32_e32 v116, v112
	s_nop 0
	v_mul_f32_e32 v124, 0x45800000, v116
	v_cndmask_b32_e32 v116, v116, v124, vcc
	v_pk_mul_f32 v[106:107], v[140:141], v[116:117] op_sel_hi:[1,0]
	v_pk_mul_f32 v[108:109], v[142:143], v[116:117] op_sel_hi:[1,0]
	v_pk_mul_f32 v[106:107], v[0:1], v[106:107]
	v_pk_mul_f32 v[108:109], v[2:3], v[108:109]
	v_pk_fma_f32 v[106:107], v[50:51], v[106:107], v[16:17]
	v_pk_fma_f32 v[108:109], v[48:49], v[108:109], v[18:19]
	v_cvt_pk_bf16_f32 v120, v106, v107
	v_cvt_pk_bf16_f32 v121, v108, v109
	global_store_dwordx2 v[122:123], v[120:121], off
	v_pk_mul_f32 v[106:107], v[144:145], v[116:117] op_sel_hi:[1,0]
	v_pk_mul_f32 v[108:109], v[146:147], v[116:117] op_sel_hi:[1,0]
	v_pk_mul_f32 v[106:107], v[4:5], v[106:107]
	v_pk_mul_f32 v[108:109], v[6:7], v[108:109]
	v_pk_fma_f32 v[106:107], v[54:55], v[106:107], v[20:21]
	v_pk_fma_f32 v[108:109], v[52:53], v[108:109], v[22:23]
	v_cvt_pk_bf16_f32 v118, v106, v107
	v_cvt_pk_bf16_f32 v119, v108, v109
	global_store_dwordx2 v[122:123], v[118:119], off offset:512
	v_pk_mul_f32 v[106:107], v[148:149], v[116:117] op_sel_hi:[1,0]
	v_pk_mul_f32 v[108:109], v[150:151], v[116:117] op_sel_hi:[1,0]
	v_pk_mul_f32 v[106:107], v[8:9], v[106:107]
	v_pk_mul_f32 v[108:109], v[10:11], v[108:109]
	v_pk_fma_f32 v[106:107], v[58:59], v[106:107], v[24:25]
	v_pk_fma_f32 v[108:109], v[56:57], v[108:109], v[26:27]
	v_cvt_pk_bf16_f32 v120, v106, v107
	v_cvt_pk_bf16_f32 v121, v108, v109
	global_store_dwordx2 v[122:123], v[120:121], off offset:1024
	v_pk_mul_f32 v[106:107], v[152:153], v[116:117] op_sel_hi:[1,0]
	v_pk_mul_f32 v[108:109], v[154:155], v[116:117] op_sel_hi:[1,0]
	v_pk_mul_f32 v[106:107], v[12:13], v[106:107]
	v_pk_mul_f32 v[108:109], v[14:15], v[108:109]
	v_pk_fma_f32 v[106:107], v[62:63], v[106:107], v[28:29]
	v_pk_fma_f32 v[108:109], v[60:61], v[108:109], v[30:31]
	v_cvt_pk_bf16_f32 v118, v106, v107
	v_cvt_pk_bf16_f32 v119, v108, v109
	global_store_dwordx2 v[122:123], v[118:119], off offset:1536
	s_and_b64 vcc, exec, s[12:13]
	s_cbranch_vccnz .Lnrm1_loop
.Lnrm1_done:
.LBB0_117:
	s_mov_b32 s19, 0x800000
	s_or_b64 exec, exec, s[0:1]
